# plus: relaxed pre-barrier lgkmcnt in A-read segments; first K-iteration peeled with zero SrcC (no accumulator zeroing movs) in swiglu and plain GEMMs
# speedup vs baseline: 1.0120x; 1.0091x over previous
.LBB0_415:
	v_writelane_b32 v250, s5, 0
	v_writelane_b32 v250, s23, 1
	v_writelane_b32 v250, s26, 2
	v_writelane_b32 v250, s27, 3
	v_writelane_b32 v250, s28, 4
	v_writelane_b32 v250, s29, 5
	v_writelane_b32 v250, s42, 6
	v_writelane_b32 v250, s43, 7
	v_writelane_b32 v250, s44, 8
	v_writelane_b32 v250, s45, 9
	v_writelane_b32 v250, s46, 10
	v_writelane_b32 v250, s47, 11
	v_writelane_b32 v250, s48, 12
	v_writelane_b32 v250, s49, 13
	v_writelane_b32 v250, s50, 14
	v_writelane_b32 v250, s51, 15
	v_writelane_b32 v250, s53, 16
	v_writelane_b32 v250, s54, 17
	v_writelane_b32 v250, s55, 18
	v_writelane_b32 v250, s56, 19
	v_writelane_b32 v250, s57, 20
	v_writelane_b32 v250, s58, 21
	v_writelane_b32 v250, s59, 22
	v_writelane_b32 v250, s60, 23
	v_writelane_b32 v250, s61, 24
	v_writelane_b32 v250, s63, 25
	v_writelane_b32 v250, s64, 26
	v_writelane_b32 v250, s65, 27
	s_add_i32 s53, s90, 0x80
	s_add_i32 s54, s52, -4
	s_add_i32 s55, s52, -3
	s_mov_b32 s56, s48
	s_add_i32 s57, s56, 0x2000
	s_add_i32 s58, s56, 0x4000
	s_add_i32 s59, s56, 0x6000
	s_add_i32 s60, s56, 0x8000
	s_add_i32 s61, s56, 0xa000
	v_readfirstlane_b32 s42, v6
	v_readfirstlane_b32 s43, v7
	v_readfirstlane_b32 s28, v4
	v_readfirstlane_b32 s29, v5
	v_readfirstlane_b32 s26, v146
	v_readfirstlane_b32 s5, v147
	v_readfirstlane_b32 s27, v148
	v_readfirstlane_b32 s23, v149
	s_add_u32 s28, s28, 0x100
	s_addc_u32 s29, s29, 0
	s_mov_b32 s63, -2
	v_mov_b32_e32 v4, 0
	s_add_u32 s44, s42, 0x100
	s_addc_u32 s45, s43, 0
	s_cmp_eq_u32 s63, s54
	s_cselect_b32 s50, s26, s44
	s_cselect_b32 s51, s5, s45
	s_cselect_b32 s48, s27, s28
	s_cselect_b32 s49, s23, s29
	s_add_i32 s64, 0, 0x10000
	v_add_u32_e32 v187, s64, v3
	s_add_i32 s65, 0, 0x14000
	ds_read_b128 v[164:167], v187
	ds_read_b128 v[168:171], v187 offset:1024
	ds_read_b128 v[188:191], v187 offset:2048
	ds_read_b128 v[192:195], v187 offset:3072
	v_add_u32_e32 v187, s65, v3
	ds_read_b128 v[196:199], v187
	ds_read_b128 v[200:203], v187 offset:1024
	ds_read_b128 v[204:207], v187 offset:2048
	ds_read_b128 v[208:211], v187 offset:3072
	s_add_u32 s46, s42, 0x80
	s_addc_u32 s47, s43, 0
	s_add_u32 s42, s42, s53
	s_addc_u32 s43, s43, 0
	s_mov_b32 m0, s60
	s_nop 0
	global_load_lds_dwordx4 v0, s[46:47]
	s_mov_b32 m0, s61
	s_nop 0
	global_load_lds_dwordx4 v142, s[46:47]
	s_add_i32 m0, s56, 0xc000
	s_nop 0
	global_load_lds_dwordx4 v0, s[42:43]
	s_add_i32 m0, s56, 0xe000
	s_nop 0
	global_load_lds_dwordx4 v142, s[42:43]
	ds_read_b128 v[212:215], v160
	ds_read_b128 v[216:219], v160 offset:1024
	ds_read_b128 v[220:223], v160 offset:2048
	ds_read_b128 v[224:227], v160 offset:3072
	ds_read_b128 v[228:231], v160 offset:4096
	ds_read_b128 v[232:235], v160 offset:5120
	ds_read_b128 v[236:239], v160 offset:6144
	ds_read_b128 v[240:243], v160 offset:7168
	s_waitcnt vmcnt(8)
	s_waitcnt lgkmcnt(8)
	s_barrier
	s_setprio 1
	s_waitcnt lgkmcnt(0)
	v_mfma_f32_16x16x32_bf16 v[128:131], v[164:167], v[212:215], 0
	v_mfma_f32_16x16x32_bf16 v[124:127], v[188:191], v[212:215], 0
	v_mfma_f32_16x16x32_bf16 v[112:115], v[164:167], v[220:223], 0
	v_mfma_f32_16x16x32_bf16 v[108:111], v[188:191], v[220:223], 0
	v_mfma_f32_16x16x32_bf16 v[96:99], v[164:167], v[228:231], 0
	v_mfma_f32_16x16x32_bf16 v[92:95], v[188:191], v[228:231], 0
	v_mfma_f32_16x16x32_bf16 v[80:83], v[164:167], v[236:239], 0
	v_mfma_f32_16x16x32_bf16 v[76:79], v[188:191], v[236:239], 0
	v_mfma_f32_16x16x32_bf16 v[128:131], v[168:171], v[216:219], v[128:131]
	v_mfma_f32_16x16x32_bf16 v[124:127], v[192:195], v[216:219], v[124:127]
	v_mfma_f32_16x16x32_bf16 v[112:115], v[168:171], v[224:227], v[112:115]
	v_mfma_f32_16x16x32_bf16 v[108:111], v[192:195], v[224:227], v[108:111]
	v_mfma_f32_16x16x32_bf16 v[96:99], v[168:171], v[232:235], v[96:99]
	v_mfma_f32_16x16x32_bf16 v[92:95], v[192:195], v[232:235], v[92:95]
	v_mfma_f32_16x16x32_bf16 v[80:83], v[168:171], v[240:243], v[80:83]
	v_mfma_f32_16x16x32_bf16 v[76:79], v[192:195], v[240:243], v[76:79]
	s_setprio 0
	s_setprio 1
	v_mfma_f32_16x16x32_bf16 v[120:123], v[196:199], v[212:215], 0
	v_mfma_f32_16x16x32_bf16 v[116:119], v[204:207], v[212:215], 0
	v_mfma_f32_16x16x32_bf16 v[104:107], v[196:199], v[220:223], 0
	v_mfma_f32_16x16x32_bf16 v[100:103], v[204:207], v[220:223], 0
	v_mfma_f32_16x16x32_bf16 v[88:91], v[196:199], v[228:231], 0
	v_mfma_f32_16x16x32_bf16 v[84:87], v[204:207], v[228:231], 0
	v_mfma_f32_16x16x32_bf16 v[72:75], v[196:199], v[236:239], 0
	v_mfma_f32_16x16x32_bf16 v[68:71], v[204:207], v[236:239], 0
	v_mfma_f32_16x16x32_bf16 v[120:123], v[200:203], v[216:219], v[120:123]
	v_mfma_f32_16x16x32_bf16 v[116:119], v[208:211], v[216:219], v[116:119]
	v_mfma_f32_16x16x32_bf16 v[104:107], v[200:203], v[224:227], v[104:107]
	v_mfma_f32_16x16x32_bf16 v[100:103], v[208:211], v[224:227], v[100:103]
	v_mfma_f32_16x16x32_bf16 v[88:91], v[200:203], v[232:235], v[88:91]
	v_mfma_f32_16x16x32_bf16 v[84:87], v[208:211], v[232:235], v[84:87]
	v_mfma_f32_16x16x32_bf16 v[72:75], v[200:203], v[240:243], v[72:75]
	v_mfma_f32_16x16x32_bf16 v[68:71], v[208:211], v[240:243], v[68:71]
	s_setprio 0
	s_barrier
	s_add_i32 s42, s64, s69
	s_mov_b32 m0, s42
	s_nop 0
	global_load_lds_dwordx4 v140, s[48:49]
	s_add_i32 m0, s42, 0x2000
	s_add_u32 s42, s48, s90
	s_addc_u32 s43, s49, 0
	s_add_i32 s64, s65, s69
	global_load_lds_dwordx4 v144, s[48:49]
	s_mov_b32 m0, s64
	s_nop 0
	global_load_lds_dwordx4 v140, s[42:43]
	s_add_i32 m0, s64, 0x2000
	s_nop 0
	global_load_lds_dwordx4 v144, s[42:43]
	ds_read_b128 v[212:215], v160 offset:16384
	ds_read_b128 v[216:219], v160 offset:17408
	ds_read_b128 v[220:223], v160 offset:18432
	ds_read_b128 v[224:227], v160 offset:19456
	ds_read_b128 v[228:231], v160 offset:20480
	ds_read_b128 v[232:235], v160 offset:21504
	ds_read_b128 v[236:239], v160 offset:22528
	ds_read_b128 v[240:243], v160 offset:23552
	s_waitcnt vmcnt(4)
	s_waitcnt lgkmcnt(0)
	s_barrier
	s_setprio 1
	s_waitcnt lgkmcnt(0)
	v_mfma_f32_16x16x32_bf16 v[64:67], v[164:167], v[212:215], 0
	v_mfma_f32_16x16x32_bf16 v[60:63], v[188:191], v[212:215], 0
	v_mfma_f32_16x16x32_bf16 v[48:51], v[164:167], v[220:223], 0
	v_mfma_f32_16x16x32_bf16 v[44:47], v[188:191], v[220:223], 0
	v_mfma_f32_16x16x32_bf16 v[32:35], v[164:167], v[228:231], 0
	v_mfma_f32_16x16x32_bf16 v[28:31], v[188:191], v[228:231], 0
	v_mfma_f32_16x16x32_bf16 v[16:19], v[164:167], v[236:239], 0
	v_mfma_f32_16x16x32_bf16 v[12:15], v[188:191], v[236:239], 0
	v_mfma_f32_16x16x32_bf16 v[64:67], v[168:171], v[216:219], v[64:67]
	v_mfma_f32_16x16x32_bf16 v[60:63], v[192:195], v[216:219], v[60:63]
	v_mfma_f32_16x16x32_bf16 v[48:51], v[168:171], v[224:227], v[48:51]
	v_mfma_f32_16x16x32_bf16 v[44:47], v[192:195], v[224:227], v[44:47]
	v_mfma_f32_16x16x32_bf16 v[32:35], v[168:171], v[232:235], v[32:35]
	v_mfma_f32_16x16x32_bf16 v[28:31], v[192:195], v[232:235], v[28:31]
	v_mfma_f32_16x16x32_bf16 v[16:19], v[168:171], v[240:243], v[16:19]
	v_mfma_f32_16x16x32_bf16 v[12:15], v[192:195], v[240:243], v[12:15]
	s_setprio 0
	s_setprio 1
	v_mfma_f32_16x16x32_bf16 v[56:59], v[196:199], v[212:215], 0
	v_mfma_f32_16x16x32_bf16 v[52:55], v[204:207], v[212:215], 0
	v_mfma_f32_16x16x32_bf16 v[40:43], v[196:199], v[220:223], 0
	v_mfma_f32_16x16x32_bf16 v[36:39], v[204:207], v[220:223], 0
	v_mfma_f32_16x16x32_bf16 v[24:27], v[196:199], v[228:231], 0
	v_mfma_f32_16x16x32_bf16 v[20:23], v[204:207], v[228:231], 0
	v_mfma_f32_16x16x32_bf16 v[8:11], v[196:199], v[236:239], 0
	v_mfma_f32_16x16x32_bf16 v[4:7], v[204:207], v[236:239], 0
	v_mfma_f32_16x16x32_bf16 v[56:59], v[200:203], v[216:219], v[56:59]
	v_mfma_f32_16x16x32_bf16 v[52:55], v[208:211], v[216:219], v[52:55]
	v_mfma_f32_16x16x32_bf16 v[40:43], v[200:203], v[224:227], v[40:43]
	v_mfma_f32_16x16x32_bf16 v[36:39], v[208:211], v[224:227], v[36:39]
	v_mfma_f32_16x16x32_bf16 v[24:27], v[200:203], v[232:235], v[24:27]
	v_mfma_f32_16x16x32_bf16 v[20:23], v[208:211], v[232:235], v[20:23]
	v_mfma_f32_16x16x32_bf16 v[8:11], v[200:203], v[240:243], v[8:11]
	v_mfma_f32_16x16x32_bf16 v[4:7], v[208:211], v[240:243], v[4:7]
	s_setprio 0
	s_barrier
	s_add_i32 s64, 0, 0x18000
	v_add_u32_e32 v187, s64, v3
	s_add_i32 s65, 0, 0x1c000
	ds_read_b128 v[164:167], v187
	ds_read_b128 v[168:171], v187 offset:1024
	ds_read_b128 v[188:191], v187 offset:2048
	ds_read_b128 v[192:195], v187 offset:3072
	v_add_u32_e32 v187, s65, v3
	ds_read_b128 v[196:199], v187
	ds_read_b128 v[200:203], v187 offset:1024
	ds_read_b128 v[204:207], v187 offset:2048
	ds_read_b128 v[208:211], v187 offset:3072
	s_add_u32 s42, s50, s90
	s_addc_u32 s43, s51, 0
	s_mov_b32 m0, s56
	s_nop 0
	global_load_lds_dwordx4 v0, s[50:51]
	s_mov_b32 m0, s57
	s_nop 0
	global_load_lds_dwordx4 v142, s[50:51]
	s_mov_b32 m0, s58
	s_nop 0
	global_load_lds_dwordx4 v0, s[42:43]
	s_mov_b32 m0, s59
	s_nop 0
	global_load_lds_dwordx4 v142, s[42:43]
	ds_read_b128 v[212:215], v160 offset:32768
	ds_read_b128 v[216:219], v160 offset:33792
	ds_read_b128 v[220:223], v160 offset:34816
	ds_read_b128 v[224:227], v160 offset:35840
	ds_read_b128 v[228:231], v160 offset:36864
	ds_read_b128 v[232:235], v160 offset:37888
	ds_read_b128 v[236:239], v160 offset:38912
	ds_read_b128 v[240:243], v160 offset:39936
	s_waitcnt vmcnt(8)
	s_waitcnt lgkmcnt(8)
	s_barrier
	s_setprio 1
	s_waitcnt lgkmcnt(0)
	v_mfma_f32_16x16x32_bf16 v[128:131], v[164:167], v[212:215], v[128:131]
	v_mfma_f32_16x16x32_bf16 v[124:127], v[188:191], v[212:215], v[124:127]
	v_mfma_f32_16x16x32_bf16 v[112:115], v[164:167], v[220:223], v[112:115]
	v_mfma_f32_16x16x32_bf16 v[108:111], v[188:191], v[220:223], v[108:111]
	v_mfma_f32_16x16x32_bf16 v[96:99], v[164:167], v[228:231], v[96:99]
	v_mfma_f32_16x16x32_bf16 v[92:95], v[188:191], v[228:231], v[92:95]
	v_mfma_f32_16x16x32_bf16 v[80:83], v[164:167], v[236:239], v[80:83]
	v_mfma_f32_16x16x32_bf16 v[76:79], v[188:191], v[236:239], v[76:79]
	v_mfma_f32_16x16x32_bf16 v[128:131], v[168:171], v[216:219], v[128:131]
	v_mfma_f32_16x16x32_bf16 v[124:127], v[192:195], v[216:219], v[124:127]
	v_mfma_f32_16x16x32_bf16 v[112:115], v[168:171], v[224:227], v[112:115]
	v_mfma_f32_16x16x32_bf16 v[108:111], v[192:195], v[224:227], v[108:111]
	v_mfma_f32_16x16x32_bf16 v[96:99], v[168:171], v[232:235], v[96:99]
	v_mfma_f32_16x16x32_bf16 v[92:95], v[192:195], v[232:235], v[92:95]
	v_mfma_f32_16x16x32_bf16 v[80:83], v[168:171], v[240:243], v[80:83]
	v_mfma_f32_16x16x32_bf16 v[76:79], v[192:195], v[240:243], v[76:79]
	s_setprio 0
	s_setprio 1
	v_mfma_f32_16x16x32_bf16 v[120:123], v[196:199], v[212:215], v[120:123]
	v_mfma_f32_16x16x32_bf16 v[116:119], v[204:207], v[212:215], v[116:119]
	v_mfma_f32_16x16x32_bf16 v[104:107], v[196:199], v[220:223], v[104:107]
	v_mfma_f32_16x16x32_bf16 v[100:103], v[204:207], v[220:223], v[100:103]
	v_mfma_f32_16x16x32_bf16 v[88:91], v[196:199], v[228:231], v[88:91]
	v_mfma_f32_16x16x32_bf16 v[84:87], v[204:207], v[228:231], v[84:87]
	v_mfma_f32_16x16x32_bf16 v[72:75], v[196:199], v[236:239], v[72:75]
	v_mfma_f32_16x16x32_bf16 v[68:71], v[204:207], v[236:239], v[68:71]
	v_mfma_f32_16x16x32_bf16 v[120:123], v[200:203], v[216:219], v[120:123]
	v_mfma_f32_16x16x32_bf16 v[116:119], v[208:211], v[216:219], v[116:119]
	v_mfma_f32_16x16x32_bf16 v[104:107], v[200:203], v[224:227], v[104:107]
	v_mfma_f32_16x16x32_bf16 v[100:103], v[208:211], v[224:227], v[100:103]
	v_mfma_f32_16x16x32_bf16 v[88:91], v[200:203], v[232:235], v[88:91]
	v_mfma_f32_16x16x32_bf16 v[84:87], v[208:211], v[232:235], v[84:87]
	v_mfma_f32_16x16x32_bf16 v[72:75], v[200:203], v[240:243], v[72:75]
	v_mfma_f32_16x16x32_bf16 v[68:71], v[208:211], v[240:243], v[68:71]
	s_setprio 0
	s_barrier
	s_add_u32 s42, s48, 0x80
	s_addc_u32 s43, s49, 0
	s_add_i32 s50, s64, s69
	s_mov_b32 m0, s50
	s_nop 0
	global_load_lds_dwordx4 v140, s[42:43]
	s_add_i32 m0, s50, 0x2000
	s_nop 0
	global_load_lds_dwordx4 v144, s[42:43]
	s_add_u32 s42, s48, s53
	s_addc_u32 s43, s49, 0
	s_add_i32 s48, s65, s69
	s_mov_b32 m0, s48
	s_nop 0
	global_load_lds_dwordx4 v140, s[42:43]
	s_add_i32 m0, s48, 0x2000
	s_nop 0
	global_load_lds_dwordx4 v144, s[42:43]
	ds_read_b128 v[212:215], v160 offset:49152
	ds_read_b128 v[216:219], v160 offset:50176
	ds_read_b128 v[220:223], v160 offset:51200
	ds_read_b128 v[224:227], v160 offset:52224
	ds_read_b128 v[228:231], v160 offset:53248
	ds_read_b128 v[232:235], v160 offset:54272
	ds_read_b128 v[236:239], v160 offset:55296
	ds_read_b128 v[240:243], v160 offset:56320
	s_waitcnt vmcnt(4)
	s_waitcnt lgkmcnt(0)
	s_barrier
	s_setprio 1
	s_waitcnt lgkmcnt(0)
	v_mfma_f32_16x16x32_bf16 v[64:67], v[164:167], v[212:215], v[64:67]
	v_mfma_f32_16x16x32_bf16 v[60:63], v[188:191], v[212:215], v[60:63]
	v_mfma_f32_16x16x32_bf16 v[48:51], v[164:167], v[220:223], v[48:51]
	v_mfma_f32_16x16x32_bf16 v[44:47], v[188:191], v[220:223], v[44:47]
	v_mfma_f32_16x16x32_bf16 v[32:35], v[164:167], v[228:231], v[32:35]
	v_mfma_f32_16x16x32_bf16 v[28:31], v[188:191], v[228:231], v[28:31]
	v_mfma_f32_16x16x32_bf16 v[16:19], v[164:167], v[236:239], v[16:19]
	v_mfma_f32_16x16x32_bf16 v[12:15], v[188:191], v[236:239], v[12:15]
	v_mfma_f32_16x16x32_bf16 v[64:67], v[168:171], v[216:219], v[64:67]
	v_mfma_f32_16x16x32_bf16 v[60:63], v[192:195], v[216:219], v[60:63]
	v_mfma_f32_16x16x32_bf16 v[48:51], v[168:171], v[224:227], v[48:51]
	v_mfma_f32_16x16x32_bf16 v[44:47], v[192:195], v[224:227], v[44:47]
	v_mfma_f32_16x16x32_bf16 v[32:35], v[168:171], v[232:235], v[32:35]
	v_mfma_f32_16x16x32_bf16 v[28:31], v[192:195], v[232:235], v[28:31]
	v_mfma_f32_16x16x32_bf16 v[16:19], v[168:171], v[240:243], v[16:19]
	v_mfma_f32_16x16x32_bf16 v[12:15], v[192:195], v[240:243], v[12:15]
	s_setprio 0
	s_setprio 1
	v_mfma_f32_16x16x32_bf16 v[56:59], v[196:199], v[212:215], v[56:59]
	v_mfma_f32_16x16x32_bf16 v[52:55], v[204:207], v[212:215], v[52:55]
	v_mfma_f32_16x16x32_bf16 v[40:43], v[196:199], v[220:223], v[40:43]
	v_mfma_f32_16x16x32_bf16 v[36:39], v[204:207], v[220:223], v[36:39]
	v_mfma_f32_16x16x32_bf16 v[24:27], v[196:199], v[228:231], v[24:27]
	v_mfma_f32_16x16x32_bf16 v[20:23], v[204:207], v[228:231], v[20:23]
	v_mfma_f32_16x16x32_bf16 v[8:11], v[196:199], v[236:239], v[8:11]
	v_mfma_f32_16x16x32_bf16 v[4:7], v[204:207], v[236:239], v[4:7]
	v_mfma_f32_16x16x32_bf16 v[56:59], v[200:203], v[216:219], v[56:59]
	v_mfma_f32_16x16x32_bf16 v[52:55], v[208:211], v[216:219], v[52:55]
	v_mfma_f32_16x16x32_bf16 v[40:43], v[200:203], v[224:227], v[40:43]
	v_mfma_f32_16x16x32_bf16 v[36:39], v[208:211], v[224:227], v[36:39]
	v_mfma_f32_16x16x32_bf16 v[24:27], v[200:203], v[232:235], v[24:27]
	v_mfma_f32_16x16x32_bf16 v[20:23], v[208:211], v[232:235], v[20:23]
	v_mfma_f32_16x16x32_bf16 v[8:11], v[200:203], v[240:243], v[8:11]
	v_mfma_f32_16x16x32_bf16 v[4:7], v[208:211], v[240:243], v[4:7]
	s_setprio 0
	s_barrier
	s_add_i32 s63, s63, 2
	s_add_u32 s28, s28, 0x100
	s_addc_u32 s29, s29, 0
	s_cmp_gt_u32 s63, s55
	s_mov_b64 s[42:43], s[44:45]

.Lg1_loop:
	s_add_u32 s44, s42, 0x100
	s_addc_u32 s45, s43, 0
	s_cmp_eq_u32 s63, s54
	s_cselect_b32 s50, s26, s44
	s_cselect_b32 s51, s5, s45
	s_cselect_b32 s48, s27, s28
	s_cselect_b32 s49, s23, s29
	s_add_i32 s64, 0, 0x10000
	v_add_u32_e32 v187, s64, v3
	s_add_i32 s65, 0, 0x14000
	ds_read_b128 v[164:167], v187
	ds_read_b128 v[168:171], v187 offset:1024
	ds_read_b128 v[188:191], v187 offset:2048
	ds_read_b128 v[192:195], v187 offset:3072
	v_add_u32_e32 v187, s65, v3
	ds_read_b128 v[196:199], v187
	ds_read_b128 v[200:203], v187 offset:1024
	ds_read_b128 v[204:207], v187 offset:2048
	ds_read_b128 v[208:211], v187 offset:3072
	s_add_u32 s46, s42, 0x80
	s_addc_u32 s47, s43, 0
	s_add_u32 s42, s42, s53
	s_addc_u32 s43, s43, 0
	s_mov_b32 m0, s60
	s_nop 0
	global_load_lds_dwordx4 v0, s[46:47]
	s_mov_b32 m0, s61
	s_nop 0
	global_load_lds_dwordx4 v142, s[46:47]
	s_add_i32 m0, s56, 0xc000
	s_nop 0
	global_load_lds_dwordx4 v0, s[42:43]
	s_add_i32 m0, s56, 0xe000
	s_nop 0
	global_load_lds_dwordx4 v142, s[42:43]
	ds_read_b128 v[212:215], v160
	ds_read_b128 v[216:219], v160 offset:1024
	ds_read_b128 v[220:223], v160 offset:2048
	ds_read_b128 v[224:227], v160 offset:3072
	ds_read_b128 v[228:231], v160 offset:4096
	ds_read_b128 v[232:235], v160 offset:5120
	ds_read_b128 v[236:239], v160 offset:6144
	ds_read_b128 v[240:243], v160 offset:7168
	s_waitcnt vmcnt(8)
	s_waitcnt lgkmcnt(8)
	s_barrier
	s_setprio 1
	s_waitcnt lgkmcnt(0)
	v_mfma_f32_16x16x32_bf16 v[128:131], v[164:167], v[212:215], v[128:131]
	v_mfma_f32_16x16x32_bf16 v[124:127], v[188:191], v[212:215], v[124:127]
	v_mfma_f32_16x16x32_bf16 v[112:115], v[164:167], v[220:223], v[112:115]
	v_mfma_f32_16x16x32_bf16 v[108:111], v[188:191], v[220:223], v[108:111]
	v_mfma_f32_16x16x32_bf16 v[96:99], v[164:167], v[228:231], v[96:99]
	v_mfma_f32_16x16x32_bf16 v[92:95], v[188:191], v[228:231], v[92:95]
	v_mfma_f32_16x16x32_bf16 v[80:83], v[164:167], v[236:239], v[80:83]
	v_mfma_f32_16x16x32_bf16 v[76:79], v[188:191], v[236:239], v[76:79]
	v_mfma_f32_16x16x32_bf16 v[128:131], v[168:171], v[216:219], v[128:131]
	v_mfma_f32_16x16x32_bf16 v[124:127], v[192:195], v[216:219], v[124:127]
	v_mfma_f32_16x16x32_bf16 v[112:115], v[168:171], v[224:227], v[112:115]
	v_mfma_f32_16x16x32_bf16 v[108:111], v[192:195], v[224:227], v[108:111]
	v_mfma_f32_16x16x32_bf16 v[96:99], v[168:171], v[232:235], v[96:99]
	v_mfma_f32_16x16x32_bf16 v[92:95], v[192:195], v[232:235], v[92:95]
	v_mfma_f32_16x16x32_bf16 v[80:83], v[168:171], v[240:243], v[80:83]
	v_mfma_f32_16x16x32_bf16 v[76:79], v[192:195], v[240:243], v[76:79]
	s_setprio 0
	s_setprio 1
	v_mfma_f32_16x16x32_bf16 v[120:123], v[196:199], v[212:215], v[120:123]
	v_mfma_f32_16x16x32_bf16 v[116:119], v[204:207], v[212:215], v[116:119]
	v_mfma_f32_16x16x32_bf16 v[104:107], v[196:199], v[220:223], v[104:107]
	v_mfma_f32_16x16x32_bf16 v[100:103], v[204:207], v[220:223], v[100:103]
	v_mfma_f32_16x16x32_bf16 v[88:91], v[196:199], v[228:231], v[88:91]
	v_mfma_f32_16x16x32_bf16 v[84:87], v[204:207], v[228:231], v[84:87]
	v_mfma_f32_16x16x32_bf16 v[72:75], v[196:199], v[236:239], v[72:75]
	v_mfma_f32_16x16x32_bf16 v[68:71], v[204:207], v[236:239], v[68:71]
	v_mfma_f32_16x16x32_bf16 v[120:123], v[200:203], v[216:219], v[120:123]
	v_mfma_f32_16x16x32_bf16 v[116:119], v[208:211], v[216:219], v[116:119]
	v_mfma_f32_16x16x32_bf16 v[104:107], v[200:203], v[224:227], v[104:107]
	v_mfma_f32_16x16x32_bf16 v[100:103], v[208:211], v[224:227], v[100:103]
	v_mfma_f32_16x16x32_bf16 v[88:91], v[200:203], v[232:235], v[88:91]
	v_mfma_f32_16x16x32_bf16 v[84:87], v[208:211], v[232:235], v[84:87]
	v_mfma_f32_16x16x32_bf16 v[72:75], v[200:203], v[240:243], v[72:75]
	v_mfma_f32_16x16x32_bf16 v[68:71], v[208:211], v[240:243], v[68:71]
	s_setprio 0
	s_barrier
	s_add_i32 s42, s64, s69
	s_mov_b32 m0, s42
	s_nop 0
	global_load_lds_dwordx4 v140, s[48:49]
	s_add_i32 m0, s42, 0x2000
	s_add_u32 s42, s48, s90
	s_addc_u32 s43, s49, 0
	s_add_i32 s64, s65, s69
	global_load_lds_dwordx4 v144, s[48:49]
	s_mov_b32 m0, s64
	s_nop 0
	global_load_lds_dwordx4 v140, s[42:43]
	s_add_i32 m0, s64, 0x2000
	s_nop 0
	global_load_lds_dwordx4 v144, s[42:43]
	ds_read_b128 v[212:215], v160 offset:16384
	ds_read_b128 v[216:219], v160 offset:17408
	ds_read_b128 v[220:223], v160 offset:18432
	ds_read_b128 v[224:227], v160 offset:19456
	ds_read_b128 v[228:231], v160 offset:20480
	ds_read_b128 v[232:235], v160 offset:21504
	ds_read_b128 v[236:239], v160 offset:22528
	ds_read_b128 v[240:243], v160 offset:23552
	s_waitcnt vmcnt(4)
	s_waitcnt lgkmcnt(0)
	s_barrier
	s_setprio 1
	s_waitcnt lgkmcnt(0)
	v_mfma_f32_16x16x32_bf16 v[64:67], v[164:167], v[212:215], v[64:67]
	v_mfma_f32_16x16x32_bf16 v[60:63], v[188:191], v[212:215], v[60:63]
	v_mfma_f32_16x16x32_bf16 v[48:51], v[164:167], v[220:223], v[48:51]
	v_mfma_f32_16x16x32_bf16 v[44:47], v[188:191], v[220:223], v[44:47]
	v_mfma_f32_16x16x32_bf16 v[32:35], v[164:167], v[228:231], v[32:35]
	v_mfma_f32_16x16x32_bf16 v[28:31], v[188:191], v[228:231], v[28:31]
	v_mfma_f32_16x16x32_bf16 v[16:19], v[164:167], v[236:239], v[16:19]
	v_mfma_f32_16x16x32_bf16 v[12:15], v[188:191], v[236:239], v[12:15]
	v_mfma_f32_16x16x32_bf16 v[64:67], v[168:171], v[216:219], v[64:67]
	v_mfma_f32_16x16x32_bf16 v[60:63], v[192:195], v[216:219], v[60:63]
	v_mfma_f32_16x16x32_bf16 v[48:51], v[168:171], v[224:227], v[48:51]
	v_mfma_f32_16x16x32_bf16 v[44:47], v[192:195], v[224:227], v[44:47]
	v_mfma_f32_16x16x32_bf16 v[32:35], v[168:171], v[232:235], v[32:35]
	v_mfma_f32_16x16x32_bf16 v[28:31], v[192:195], v[232:235], v[28:31]
	v_mfma_f32_16x16x32_bf16 v[16:19], v[168:171], v[240:243], v[16:19]
	v_mfma_f32_16x16x32_bf16 v[12:15], v[192:195], v[240:243], v[12:15]
	s_setprio 0
	s_setprio 1
	v_mfma_f32_16x16x32_bf16 v[56:59], v[196:199], v[212:215], v[56:59]
	v_mfma_f32_16x16x32_bf16 v[52:55], v[204:207], v[212:215], v[52:55]
	v_mfma_f32_16x16x32_bf16 v[40:43], v[196:199], v[220:223], v[40:43]
	v_mfma_f32_16x16x32_bf16 v[36:39], v[204:207], v[220:223], v[36:39]
	v_mfma_f32_16x16x32_bf16 v[24:27], v[196:199], v[228:231], v[24:27]
	v_mfma_f32_16x16x32_bf16 v[20:23], v[204:207], v[228:231], v[20:23]
	v_mfma_f32_16x16x32_bf16 v[8:11], v[196:199], v[236:239], v[8:11]
	v_mfma_f32_16x16x32_bf16 v[4:7], v[204:207], v[236:239], v[4:7]
	v_mfma_f32_16x16x32_bf16 v[56:59], v[200:203], v[216:219], v[56:59]
	v_mfma_f32_16x16x32_bf16 v[52:55], v[208:211], v[216:219], v[52:55]
	v_mfma_f32_16x16x32_bf16 v[40:43], v[200:203], v[224:227], v[40:43]
	v_mfma_f32_16x16x32_bf16 v[36:39], v[208:211], v[224:227], v[36:39]
	v_mfma_f32_16x16x32_bf16 v[24:27], v[200:203], v[232:235], v[24:27]
	v_mfma_f32_16x16x32_bf16 v[20:23], v[208:211], v[232:235], v[20:23]
	v_mfma_f32_16x16x32_bf16 v[8:11], v[200:203], v[240:243], v[8:11]
	v_mfma_f32_16x16x32_bf16 v[4:7], v[208:211], v[240:243], v[4:7]
	s_setprio 0
	s_barrier
	s_add_i32 s64, 0, 0x18000
	v_add_u32_e32 v187, s64, v3
	s_add_i32 s65, 0, 0x1c000
	ds_read_b128 v[164:167], v187
	ds_read_b128 v[168:171], v187 offset:1024
	ds_read_b128 v[188:191], v187 offset:2048
	ds_read_b128 v[192:195], v187 offset:3072
	v_add_u32_e32 v187, s65, v3
	ds_read_b128 v[196:199], v187
	ds_read_b128 v[200:203], v187 offset:1024
	ds_read_b128 v[204:207], v187 offset:2048
	ds_read_b128 v[208:211], v187 offset:3072
	s_add_u32 s42, s50, s90
	s_addc_u32 s43, s51, 0
	s_mov_b32 m0, s56
	s_nop 0
	global_load_lds_dwordx4 v0, s[50:51]
	s_mov_b32 m0, s57
	s_nop 0
	global_load_lds_dwordx4 v142, s[50:51]
	s_mov_b32 m0, s58
	s_nop 0
	global_load_lds_dwordx4 v0, s[42:43]
	s_mov_b32 m0, s59
	s_nop 0
	global_load_lds_dwordx4 v142, s[42:43]
	ds_read_b128 v[212:215], v160 offset:32768
	ds_read_b128 v[216:219], v160 offset:33792
	ds_read_b128 v[220:223], v160 offset:34816
	ds_read_b128 v[224:227], v160 offset:35840
	ds_read_b128 v[228:231], v160 offset:36864
	ds_read_b128 v[232:235], v160 offset:37888
	ds_read_b128 v[236:239], v160 offset:38912
	ds_read_b128 v[240:243], v160 offset:39936
	s_waitcnt vmcnt(8)
	s_waitcnt lgkmcnt(8)
	s_barrier
	s_setprio 1
	s_waitcnt lgkmcnt(0)
	v_mfma_f32_16x16x32_bf16 v[128:131], v[164:167], v[212:215], v[128:131]
	v_mfma_f32_16x16x32_bf16 v[124:127], v[188:191], v[212:215], v[124:127]
	v_mfma_f32_16x16x32_bf16 v[112:115], v[164:167], v[220:223], v[112:115]
	v_mfma_f32_16x16x32_bf16 v[108:111], v[188:191], v[220:223], v[108:111]
	v_mfma_f32_16x16x32_bf16 v[96:99], v[164:167], v[228:231], v[96:99]
	v_mfma_f32_16x16x32_bf16 v[92:95], v[188:191], v[228:231], v[92:95]
	v_mfma_f32_16x16x32_bf16 v[80:83], v[164:167], v[236:239], v[80:83]
	v_mfma_f32_16x16x32_bf16 v[76:79], v[188:191], v[236:239], v[76:79]
	v_mfma_f32_16x16x32_bf16 v[128:131], v[168:171], v[216:219], v[128:131]
	v_mfma_f32_16x16x32_bf16 v[124:127], v[192:195], v[216:219], v[124:127]
	v_mfma_f32_16x16x32_bf16 v[112:115], v[168:171], v[224:227], v[112:115]
	v_mfma_f32_16x16x32_bf16 v[108:111], v[192:195], v[224:227], v[108:111]
	v_mfma_f32_16x16x32_bf16 v[96:99], v[168:171], v[232:235], v[96:99]
	v_mfma_f32_16x16x32_bf16 v[92:95], v[192:195], v[232:235], v[92:95]
	v_mfma_f32_16x16x32_bf16 v[80:83], v[168:171], v[240:243], v[80:83]
	v_mfma_f32_16x16x32_bf16 v[76:79], v[192:195], v[240:243], v[76:79]
	s_setprio 0
	s_setprio 1
	v_mfma_f32_16x16x32_bf16 v[120:123], v[196:199], v[212:215], v[120:123]
	v_mfma_f32_16x16x32_bf16 v[116:119], v[204:207], v[212:215], v[116:119]
	v_mfma_f32_16x16x32_bf16 v[104:107], v[196:199], v[220:223], v[104:107]
	v_mfma_f32_16x16x32_bf16 v[100:103], v[204:207], v[220:223], v[100:103]
	v_mfma_f32_16x16x32_bf16 v[88:91], v[196:199], v[228:231], v[88:91]
	v_mfma_f32_16x16x32_bf16 v[84:87], v[204:207], v[228:231], v[84:87]
	v_mfma_f32_16x16x32_bf16 v[72:75], v[196:199], v[236:239], v[72:75]
	v_mfma_f32_16x16x32_bf16 v[68:71], v[204:207], v[236:239], v[68:71]
	v_mfma_f32_16x16x32_bf16 v[120:123], v[200:203], v[216:219], v[120:123]
	v_mfma_f32_16x16x32_bf16 v[116:119], v[208:211], v[216:219], v[116:119]
	v_mfma_f32_16x16x32_bf16 v[104:107], v[200:203], v[224:227], v[104:107]
	v_mfma_f32_16x16x32_bf16 v[100:103], v[208:211], v[224:227], v[100:103]
	v_mfma_f32_16x16x32_bf16 v[88:91], v[200:203], v[232:235], v[88:91]
	v_mfma_f32_16x16x32_bf16 v[84:87], v[208:211], v[232:235], v[84:87]
	v_mfma_f32_16x16x32_bf16 v[72:75], v[200:203], v[240:243], v[72:75]
	v_mfma_f32_16x16x32_bf16 v[68:71], v[208:211], v[240:243], v[68:71]
	s_setprio 0
	s_barrier
	s_add_u32 s42, s48, 0x80
	s_addc_u32 s43, s49, 0
	s_add_i32 s50, s64, s69
	s_mov_b32 m0, s50
	s_nop 0
	global_load_lds_dwordx4 v140, s[42:43]
	s_add_i32 m0, s50, 0x2000
	s_nop 0
	global_load_lds_dwordx4 v144, s[42:43]
	s_add_u32 s42, s48, s53
	s_addc_u32 s43, s49, 0
	s_add_i32 s48, s65, s69
	s_mov_b32 m0, s48
	s_nop 0
	global_load_lds_dwordx4 v140, s[42:43]
	s_add_i32 m0, s48, 0x2000
	s_nop 0
	global_load_lds_dwordx4 v144, s[42:43]
	ds_read_b128 v[212:215], v160 offset:49152
	ds_read_b128 v[216:219], v160 offset:50176
	ds_read_b128 v[220:223], v160 offset:51200
	ds_read_b128 v[224:227], v160 offset:52224
	ds_read_b128 v[228:231], v160 offset:53248
	ds_read_b128 v[232:235], v160 offset:54272
	ds_read_b128 v[236:239], v160 offset:55296
	ds_read_b128 v[240:243], v160 offset:56320
	s_waitcnt vmcnt(4)
	s_waitcnt lgkmcnt(0)
	s_barrier
	s_setprio 1
	s_waitcnt lgkmcnt(0)
	v_mfma_f32_16x16x32_bf16 v[64:67], v[164:167], v[212:215], v[64:67]
	v_mfma_f32_16x16x32_bf16 v[60:63], v[188:191], v[212:215], v[60:63]
	v_mfma_f32_16x16x32_bf16 v[48:51], v[164:167], v[220:223], v[48:51]
	v_mfma_f32_16x16x32_bf16 v[44:47], v[188:191], v[220:223], v[44:47]
	v_mfma_f32_16x16x32_bf16 v[32:35], v[164:167], v[228:231], v[32:35]
	v_mfma_f32_16x16x32_bf16 v[28:31], v[188:191], v[228:231], v[28:31]
	v_mfma_f32_16x16x32_bf16 v[16:19], v[164:167], v[236:239], v[16:19]
	v_mfma_f32_16x16x32_bf16 v[12:15], v[188:191], v[236:239], v[12:15]
	v_mfma_f32_16x16x32_bf16 v[64:67], v[168:171], v[216:219], v[64:67]
	v_mfma_f32_16x16x32_bf16 v[60:63], v[192:195], v[216:219], v[60:63]
	v_mfma_f32_16x16x32_bf16 v[48:51], v[168:171], v[224:227], v[48:51]
	v_mfma_f32_16x16x32_bf16 v[44:47], v[192:195], v[224:227], v[44:47]
	v_mfma_f32_16x16x32_bf16 v[32:35], v[168:171], v[232:235], v[32:35]
	v_mfma_f32_16x16x32_bf16 v[28:31], v[192:195], v[232:235], v[28:31]
	v_mfma_f32_16x16x32_bf16 v[16:19], v[168:171], v[240:243], v[16:19]
	v_mfma_f32_16x16x32_bf16 v[12:15], v[192:195], v[240:243], v[12:15]
	s_setprio 0
	s_setprio 1
	v_mfma_f32_16x16x32_bf16 v[56:59], v[196:199], v[212:215], v[56:59]
	v_mfma_f32_16x16x32_bf16 v[52:55], v[204:207], v[212:215], v[52:55]
	v_mfma_f32_16x16x32_bf16 v[40:43], v[196:199], v[220:223], v[40:43]
	v_mfma_f32_16x16x32_bf16 v[36:39], v[204:207], v[220:223], v[36:39]
	v_mfma_f32_16x16x32_bf16 v[24:27], v[196:199], v[228:231], v[24:27]
	v_mfma_f32_16x16x32_bf16 v[20:23], v[204:207], v[228:231], v[20:23]
	v_mfma_f32_16x16x32_bf16 v[8:11], v[196:199], v[236:239], v[8:11]
	v_mfma_f32_16x16x32_bf16 v[4:7], v[204:207], v[236:239], v[4:7]
	v_mfma_f32_16x16x32_bf16 v[56:59], v[200:203], v[216:219], v[56:59]
	v_mfma_f32_16x16x32_bf16 v[52:55], v[208:211], v[216:219], v[52:55]
	v_mfma_f32_16x16x32_bf16 v[40:43], v[200:203], v[224:227], v[40:43]
	v_mfma_f32_16x16x32_bf16 v[36:39], v[208:211], v[224:227], v[36:39]
	v_mfma_f32_16x16x32_bf16 v[24:27], v[200:203], v[232:235], v[24:27]
	v_mfma_f32_16x16x32_bf16 v[20:23], v[208:211], v[232:235], v[20:23]
	v_mfma_f32_16x16x32_bf16 v[8:11], v[200:203], v[240:243], v[8:11]
	v_mfma_f32_16x16x32_bf16 v[4:7], v[208:211], v[240:243], v[4:7]
	s_setprio 0
	s_barrier
	s_add_i32 s63, s63, 2
	s_add_u32 s28, s28, 0x100
	s_addc_u32 s29, s29, 0
	s_cmp_gt_u32 s63, s55
	s_mov_b64 s[42:43], s[44:45]
	s_cbranch_scc0 .Lg1_loop
	v_readlane_b32 s5, v250, 0
	v_readlane_b32 s23, v250, 1
	v_readlane_b32 s26, v250, 2
	v_readlane_b32 s27, v250, 3
	v_readlane_b32 s28, v250, 4
	v_readlane_b32 s29, v250, 5
	v_readlane_b32 s42, v250, 6
	v_readlane_b32 s43, v250, 7
	v_readlane_b32 s44, v250, 8
	v_readlane_b32 s45, v250, 9
	v_readlane_b32 s46, v250, 10
	v_readlane_b32 s47, v250, 11
	v_readlane_b32 s48, v250, 12
	v_readlane_b32 s49, v250, 13
	v_readlane_b32 s50, v250, 14
	v_readlane_b32 s51, v250, 15
	v_readlane_b32 s53, v250, 16
	v_readlane_b32 s54, v250, 17
	v_readlane_b32 s55, v250, 18
	v_readlane_b32 s56, v250, 19
	v_readlane_b32 s57, v250, 20
	v_readlane_b32 s58, v250, 21
	v_readlane_b32 s59, v250, 22
	v_readlane_b32 s60, v250, 23
	v_readlane_b32 s61, v250, 24
	v_readlane_b32 s63, v250, 25
	v_readlane_b32 s64, v250, 26
	v_readlane_b32 s65, v250, 27
	s_and_b64 vcc, exec, s[14:15]
	s_cbranch_vccz .LBB0_419
	s_barrier

.LBB0_499:
	s_ashr_i32 s5, s4, 31
	s_lshl_b64 s[24:25], s[4:5], 19
	s_add_u32 s24, s52, s24
	s_addc_u32 s25, s53, s25
	s_and_b64 s[26:27], s[40:41], exec
	s_cselect_b32 s5, s25, s43
	s_cselect_b32 s26, s24, s42
	s_ashr_i32 s23, s22, 31
	s_lshl_b64 s[28:29], s[22:23], 19
	s_add_u32 s36, s54, s28
	s_addc_u32 s37, s55, s29
	s_and_b64 s[28:29], s[40:41], exec
	s_cselect_b32 s23, s37, s45
	s_cselect_b32 s27, s36, s44
	s_add_u32 s28, s44, 0x100
	v_mov_b32_e32 v4, 0
	s_addc_u32 s29, s45, 0
	s_mov_b32 s63, -2
	s_add_u32 s44, s42, 0x100
	s_addc_u32 s45, s43, 0
	s_cmp_eq_u32 s63, 12
	s_cselect_b32 s50, s26, s44
	s_cselect_b32 s51, s5, s45
	s_cselect_b32 s48, s27, s28
	s_cselect_b32 s49, s23, s29
	s_add_i32 s64, 0, 0x10000
	v_add_u32_e32 v138, s64, v3
	s_add_i32 s65, 0, 0x14000
	ds_read_b128 v[146:149], v138
	ds_read_b128 v[150:153], v138 offset:1024
	ds_read_b128 v[154:157], v138 offset:2048
	ds_read_b128 v[158:161], v138 offset:3072
	v_add_u32_e32 v138, s65, v3
	ds_read_b128 v[162:165], v138
	ds_read_b128 v[166:169], v138 offset:1024
	ds_read_b128 v[170:173], v138 offset:2048
	ds_read_b128 v[186:189], v138 offset:3072
	s_add_u32 s46, s42, 0x80
	s_addc_u32 s47, s43, 0
	s_add_u32 s42, s42, 0x40080
	s_addc_u32 s43, s43, 0
	s_mov_b32 m0, s60
	s_nop 0
	global_load_lds_dwordx4 v144, s[46:47]
	s_mov_b32 m0, s61
	s_nop 0
	global_load_lds_dwordx4 v140, s[46:47]
	s_add_i32 m0, s56, 0xc000
	s_nop 0
	global_load_lds_dwordx4 v144, s[42:43]
	s_add_i32 m0, s56, 0xe000
	s_nop 0
	global_load_lds_dwordx4 v140, s[42:43]
	ds_read_b128 v[190:193], v132
	ds_read_b128 v[194:197], v132 offset:1024
	ds_read_b128 v[198:201], v132 offset:2048
	ds_read_b128 v[202:205], v132 offset:3072
	ds_read_b128 v[206:209], v132 offset:4096
	ds_read_b128 v[210:213], v132 offset:5120
	ds_read_b128 v[214:217], v132 offset:6144
	ds_read_b128 v[218:221], v132 offset:7168
	s_waitcnt vmcnt(8)
	s_waitcnt lgkmcnt(8)
	s_barrier
	s_setprio 1
	s_waitcnt lgkmcnt(0)
	v_mfma_f32_16x16x32_bf16 v[128:131], v[146:149], v[190:193], 0
	v_mfma_f32_16x16x32_bf16 v[124:127], v[154:157], v[190:193], 0
	v_mfma_f32_16x16x32_bf16 v[112:115], v[146:149], v[198:201], 0
	v_mfma_f32_16x16x32_bf16 v[108:111], v[154:157], v[198:201], 0
	v_mfma_f32_16x16x32_bf16 v[96:99], v[146:149], v[206:209], 0
	v_mfma_f32_16x16x32_bf16 v[92:95], v[154:157], v[206:209], 0
	v_mfma_f32_16x16x32_bf16 v[80:83], v[146:149], v[214:217], 0
	v_mfma_f32_16x16x32_bf16 v[76:79], v[154:157], v[214:217], 0
	v_mfma_f32_16x16x32_bf16 v[128:131], v[150:153], v[194:197], v[128:131]
	v_mfma_f32_16x16x32_bf16 v[124:127], v[158:161], v[194:197], v[124:127]
	v_mfma_f32_16x16x32_bf16 v[112:115], v[150:153], v[202:205], v[112:115]
	v_mfma_f32_16x16x32_bf16 v[108:111], v[158:161], v[202:205], v[108:111]
	v_mfma_f32_16x16x32_bf16 v[96:99], v[150:153], v[210:213], v[96:99]
	v_mfma_f32_16x16x32_bf16 v[92:95], v[158:161], v[210:213], v[92:95]
	v_mfma_f32_16x16x32_bf16 v[80:83], v[150:153], v[218:221], v[80:83]
	v_mfma_f32_16x16x32_bf16 v[76:79], v[158:161], v[218:221], v[76:79]
	s_setprio 0
	s_setprio 1
	v_mfma_f32_16x16x32_bf16 v[120:123], v[162:165], v[190:193], 0
	v_mfma_f32_16x16x32_bf16 v[116:119], v[170:173], v[190:193], 0
	v_mfma_f32_16x16x32_bf16 v[104:107], v[162:165], v[198:201], 0
	v_mfma_f32_16x16x32_bf16 v[100:103], v[170:173], v[198:201], 0
	v_mfma_f32_16x16x32_bf16 v[88:91], v[162:165], v[206:209], 0
	v_mfma_f32_16x16x32_bf16 v[84:87], v[170:173], v[206:209], 0
	v_mfma_f32_16x16x32_bf16 v[72:75], v[162:165], v[214:217], 0
	v_mfma_f32_16x16x32_bf16 v[68:71], v[170:173], v[214:217], 0
	v_mfma_f32_16x16x32_bf16 v[120:123], v[166:169], v[194:197], v[120:123]
	v_mfma_f32_16x16x32_bf16 v[116:119], v[186:189], v[194:197], v[116:119]
	v_mfma_f32_16x16x32_bf16 v[104:107], v[166:169], v[202:205], v[104:107]
	v_mfma_f32_16x16x32_bf16 v[100:103], v[186:189], v[202:205], v[100:103]
	v_mfma_f32_16x16x32_bf16 v[88:91], v[166:169], v[210:213], v[88:91]
	v_mfma_f32_16x16x32_bf16 v[84:87], v[186:189], v[210:213], v[84:87]
	v_mfma_f32_16x16x32_bf16 v[72:75], v[166:169], v[218:221], v[72:75]
	v_mfma_f32_16x16x32_bf16 v[68:71], v[186:189], v[218:221], v[68:71]
	s_setprio 0
	s_barrier
	s_add_i32 s42, s64, s69
	s_mov_b32 m0, s42
	s_nop 0
	global_load_lds_dwordx4 v142, s[48:49]
	s_add_i32 m0, s42, 0x2000
	s_add_u32 s42, s48, 0x40000
	s_addc_u32 s43, s49, 0
	s_add_i32 s64, s65, s69
	global_load_lds_dwordx4 v0, s[48:49]
	s_mov_b32 m0, s64
	s_nop 0
	global_load_lds_dwordx4 v142, s[42:43]
	s_add_i32 m0, s64, 0x2000
	s_nop 0
	global_load_lds_dwordx4 v0, s[42:43]
	ds_read_b128 v[190:193], v132 offset:16384
	ds_read_b128 v[194:197], v132 offset:17408
	ds_read_b128 v[198:201], v132 offset:18432
	ds_read_b128 v[202:205], v132 offset:19456
	ds_read_b128 v[206:209], v132 offset:20480
	ds_read_b128 v[210:213], v132 offset:21504
	ds_read_b128 v[214:217], v132 offset:22528
	ds_read_b128 v[218:221], v132 offset:23552
	s_waitcnt vmcnt(4)
	s_waitcnt lgkmcnt(0)
	s_barrier
	s_setprio 1
	s_waitcnt lgkmcnt(0)
	v_mfma_f32_16x16x32_bf16 v[64:67], v[146:149], v[190:193], 0
	v_mfma_f32_16x16x32_bf16 v[60:63], v[154:157], v[190:193], 0
	v_mfma_f32_16x16x32_bf16 v[48:51], v[146:149], v[198:201], 0
	v_mfma_f32_16x16x32_bf16 v[44:47], v[154:157], v[198:201], 0
	v_mfma_f32_16x16x32_bf16 v[32:35], v[146:149], v[206:209], 0
	v_mfma_f32_16x16x32_bf16 v[28:31], v[154:157], v[206:209], 0
	v_mfma_f32_16x16x32_bf16 v[16:19], v[146:149], v[214:217], 0
	v_mfma_f32_16x16x32_bf16 v[12:15], v[154:157], v[214:217], 0
	v_mfma_f32_16x16x32_bf16 v[64:67], v[150:153], v[194:197], v[64:67]
	v_mfma_f32_16x16x32_bf16 v[60:63], v[158:161], v[194:197], v[60:63]
	v_mfma_f32_16x16x32_bf16 v[48:51], v[150:153], v[202:205], v[48:51]
	v_mfma_f32_16x16x32_bf16 v[44:47], v[158:161], v[202:205], v[44:47]
	v_mfma_f32_16x16x32_bf16 v[32:35], v[150:153], v[210:213], v[32:35]
	v_mfma_f32_16x16x32_bf16 v[28:31], v[158:161], v[210:213], v[28:31]
	v_mfma_f32_16x16x32_bf16 v[16:19], v[150:153], v[218:221], v[16:19]
	v_mfma_f32_16x16x32_bf16 v[12:15], v[158:161], v[218:221], v[12:15]
	s_setprio 0
	s_setprio 1
	v_mfma_f32_16x16x32_bf16 v[56:59], v[162:165], v[190:193], 0
	v_mfma_f32_16x16x32_bf16 v[52:55], v[170:173], v[190:193], 0
	v_mfma_f32_16x16x32_bf16 v[40:43], v[162:165], v[198:201], 0
	v_mfma_f32_16x16x32_bf16 v[36:39], v[170:173], v[198:201], 0
	v_mfma_f32_16x16x32_bf16 v[24:27], v[162:165], v[206:209], 0
	v_mfma_f32_16x16x32_bf16 v[20:23], v[170:173], v[206:209], 0
	v_mfma_f32_16x16x32_bf16 v[8:11], v[162:165], v[214:217], 0
	v_mfma_f32_16x16x32_bf16 v[4:7], v[170:173], v[214:217], 0
	v_mfma_f32_16x16x32_bf16 v[56:59], v[166:169], v[194:197], v[56:59]
	v_mfma_f32_16x16x32_bf16 v[52:55], v[186:189], v[194:197], v[52:55]
	v_mfma_f32_16x16x32_bf16 v[40:43], v[166:169], v[202:205], v[40:43]
	v_mfma_f32_16x16x32_bf16 v[36:39], v[186:189], v[202:205], v[36:39]
	v_mfma_f32_16x16x32_bf16 v[24:27], v[166:169], v[210:213], v[24:27]
	v_mfma_f32_16x16x32_bf16 v[20:23], v[186:189], v[210:213], v[20:23]
	v_mfma_f32_16x16x32_bf16 v[8:11], v[166:169], v[218:221], v[8:11]
	v_mfma_f32_16x16x32_bf16 v[4:7], v[186:189], v[218:221], v[4:7]
	s_setprio 0
	s_barrier
	s_add_i32 s64, 0, 0x18000
	v_add_u32_e32 v138, s64, v3
	s_add_i32 s65, 0, 0x1c000
	ds_read_b128 v[146:149], v138
	ds_read_b128 v[150:153], v138 offset:1024
	ds_read_b128 v[154:157], v138 offset:2048
	ds_read_b128 v[158:161], v138 offset:3072
	v_add_u32_e32 v138, s65, v3
	ds_read_b128 v[162:165], v138
	ds_read_b128 v[166:169], v138 offset:1024
	ds_read_b128 v[170:173], v138 offset:2048
	ds_read_b128 v[186:189], v138 offset:3072
	s_add_u32 s42, s50, 0x40000
	s_addc_u32 s43, s51, 0
	s_mov_b32 m0, s56
	s_nop 0
	global_load_lds_dwordx4 v144, s[50:51]
	s_mov_b32 m0, s57
	s_nop 0
	global_load_lds_dwordx4 v140, s[50:51]
	s_mov_b32 m0, s58
	s_nop 0
	global_load_lds_dwordx4 v144, s[42:43]
	s_mov_b32 m0, s59
	s_nop 0
	global_load_lds_dwordx4 v140, s[42:43]
	ds_read_b128 v[190:193], v132 offset:32768
	ds_read_b128 v[194:197], v132 offset:33792
	ds_read_b128 v[198:201], v132 offset:34816
	ds_read_b128 v[202:205], v132 offset:35840
	ds_read_b128 v[206:209], v132 offset:36864
	ds_read_b128 v[210:213], v132 offset:37888
	ds_read_b128 v[214:217], v132 offset:38912
	ds_read_b128 v[218:221], v132 offset:39936
	s_waitcnt vmcnt(8)
	s_waitcnt lgkmcnt(8)
	s_barrier
	s_setprio 1
	s_waitcnt lgkmcnt(0)
	v_mfma_f32_16x16x32_bf16 v[128:131], v[146:149], v[190:193], v[128:131]
	v_mfma_f32_16x16x32_bf16 v[124:127], v[154:157], v[190:193], v[124:127]
	v_mfma_f32_16x16x32_bf16 v[112:115], v[146:149], v[198:201], v[112:115]
	v_mfma_f32_16x16x32_bf16 v[108:111], v[154:157], v[198:201], v[108:111]
	v_mfma_f32_16x16x32_bf16 v[96:99], v[146:149], v[206:209], v[96:99]
	v_mfma_f32_16x16x32_bf16 v[92:95], v[154:157], v[206:209], v[92:95]
	v_mfma_f32_16x16x32_bf16 v[80:83], v[146:149], v[214:217], v[80:83]
	v_mfma_f32_16x16x32_bf16 v[76:79], v[154:157], v[214:217], v[76:79]
	v_mfma_f32_16x16x32_bf16 v[128:131], v[150:153], v[194:197], v[128:131]
	v_mfma_f32_16x16x32_bf16 v[124:127], v[158:161], v[194:197], v[124:127]
	v_mfma_f32_16x16x32_bf16 v[112:115], v[150:153], v[202:205], v[112:115]
	v_mfma_f32_16x16x32_bf16 v[108:111], v[158:161], v[202:205], v[108:111]
	v_mfma_f32_16x16x32_bf16 v[96:99], v[150:153], v[210:213], v[96:99]
	v_mfma_f32_16x16x32_bf16 v[92:95], v[158:161], v[210:213], v[92:95]
	v_mfma_f32_16x16x32_bf16 v[80:83], v[150:153], v[218:221], v[80:83]
	v_mfma_f32_16x16x32_bf16 v[76:79], v[158:161], v[218:221], v[76:79]
	s_setprio 0
	s_setprio 1
	v_mfma_f32_16x16x32_bf16 v[120:123], v[162:165], v[190:193], v[120:123]
	v_mfma_f32_16x16x32_bf16 v[116:119], v[170:173], v[190:193], v[116:119]
	v_mfma_f32_16x16x32_bf16 v[104:107], v[162:165], v[198:201], v[104:107]
	v_mfma_f32_16x16x32_bf16 v[100:103], v[170:173], v[198:201], v[100:103]
	v_mfma_f32_16x16x32_bf16 v[88:91], v[162:165], v[206:209], v[88:91]
	v_mfma_f32_16x16x32_bf16 v[84:87], v[170:173], v[206:209], v[84:87]
	v_mfma_f32_16x16x32_bf16 v[72:75], v[162:165], v[214:217], v[72:75]
	v_mfma_f32_16x16x32_bf16 v[68:71], v[170:173], v[214:217], v[68:71]
	v_mfma_f32_16x16x32_bf16 v[120:123], v[166:169], v[194:197], v[120:123]
	v_mfma_f32_16x16x32_bf16 v[116:119], v[186:189], v[194:197], v[116:119]
	v_mfma_f32_16x16x32_bf16 v[104:107], v[166:169], v[202:205], v[104:107]
	v_mfma_f32_16x16x32_bf16 v[100:103], v[186:189], v[202:205], v[100:103]
	v_mfma_f32_16x16x32_bf16 v[88:91], v[166:169], v[210:213], v[88:91]
	v_mfma_f32_16x16x32_bf16 v[84:87], v[186:189], v[210:213], v[84:87]
	v_mfma_f32_16x16x32_bf16 v[72:75], v[166:169], v[218:221], v[72:75]
	v_mfma_f32_16x16x32_bf16 v[68:71], v[186:189], v[218:221], v[68:71]
	s_setprio 0
	s_barrier
	s_add_u32 s42, s48, 0x80
	s_addc_u32 s43, s49, 0
	s_add_i32 s50, s64, s69
	s_mov_b32 m0, s50
	s_nop 0
	global_load_lds_dwordx4 v142, s[42:43]
	s_add_i32 m0, s50, 0x2000
	s_nop 0
	global_load_lds_dwordx4 v0, s[42:43]
	s_add_u32 s42, s48, 0x40080
	s_addc_u32 s43, s49, 0
	s_add_i32 s48, s65, s69
	s_mov_b32 m0, s48
	s_nop 0
	global_load_lds_dwordx4 v142, s[42:43]
	s_add_i32 m0, s48, 0x2000
	s_nop 0
	global_load_lds_dwordx4 v0, s[42:43]
	ds_read_b128 v[190:193], v132 offset:49152
	ds_read_b128 v[194:197], v132 offset:50176
	ds_read_b128 v[198:201], v132 offset:51200
	ds_read_b128 v[202:205], v132 offset:52224
	ds_read_b128 v[206:209], v132 offset:53248
	ds_read_b128 v[210:213], v132 offset:54272
	ds_read_b128 v[214:217], v132 offset:55296
	ds_read_b128 v[218:221], v132 offset:56320
	s_waitcnt vmcnt(4)
	s_waitcnt lgkmcnt(0)
	s_barrier
	s_setprio 1
	s_waitcnt lgkmcnt(0)
	v_mfma_f32_16x16x32_bf16 v[64:67], v[146:149], v[190:193], v[64:67]
	v_mfma_f32_16x16x32_bf16 v[60:63], v[154:157], v[190:193], v[60:63]
	v_mfma_f32_16x16x32_bf16 v[48:51], v[146:149], v[198:201], v[48:51]
	v_mfma_f32_16x16x32_bf16 v[44:47], v[154:157], v[198:201], v[44:47]
	v_mfma_f32_16x16x32_bf16 v[32:35], v[146:149], v[206:209], v[32:35]
	v_mfma_f32_16x16x32_bf16 v[28:31], v[154:157], v[206:209], v[28:31]
	v_mfma_f32_16x16x32_bf16 v[16:19], v[146:149], v[214:217], v[16:19]
	v_mfma_f32_16x16x32_bf16 v[12:15], v[154:157], v[214:217], v[12:15]
	v_mfma_f32_16x16x32_bf16 v[64:67], v[150:153], v[194:197], v[64:67]
	v_mfma_f32_16x16x32_bf16 v[60:63], v[158:161], v[194:197], v[60:63]
	v_mfma_f32_16x16x32_bf16 v[48:51], v[150:153], v[202:205], v[48:51]
	v_mfma_f32_16x16x32_bf16 v[44:47], v[158:161], v[202:205], v[44:47]
	v_mfma_f32_16x16x32_bf16 v[32:35], v[150:153], v[210:213], v[32:35]
	v_mfma_f32_16x16x32_bf16 v[28:31], v[158:161], v[210:213], v[28:31]
	v_mfma_f32_16x16x32_bf16 v[16:19], v[150:153], v[218:221], v[16:19]
	v_mfma_f32_16x16x32_bf16 v[12:15], v[158:161], v[218:221], v[12:15]
	s_setprio 0
	s_setprio 1
	v_mfma_f32_16x16x32_bf16 v[56:59], v[162:165], v[190:193], v[56:59]
	v_mfma_f32_16x16x32_bf16 v[52:55], v[170:173], v[190:193], v[52:55]
	v_mfma_f32_16x16x32_bf16 v[40:43], v[162:165], v[198:201], v[40:43]
	v_mfma_f32_16x16x32_bf16 v[36:39], v[170:173], v[198:201], v[36:39]
	v_mfma_f32_16x16x32_bf16 v[24:27], v[162:165], v[206:209], v[24:27]
	v_mfma_f32_16x16x32_bf16 v[20:23], v[170:173], v[206:209], v[20:23]
	v_mfma_f32_16x16x32_bf16 v[8:11], v[162:165], v[214:217], v[8:11]
	v_mfma_f32_16x16x32_bf16 v[4:7], v[170:173], v[214:217], v[4:7]
	v_mfma_f32_16x16x32_bf16 v[56:59], v[166:169], v[194:197], v[56:59]
	v_mfma_f32_16x16x32_bf16 v[52:55], v[186:189], v[194:197], v[52:55]
	v_mfma_f32_16x16x32_bf16 v[40:43], v[166:169], v[202:205], v[40:43]
	v_mfma_f32_16x16x32_bf16 v[36:39], v[186:189], v[202:205], v[36:39]
	v_mfma_f32_16x16x32_bf16 v[24:27], v[166:169], v[210:213], v[24:27]
	v_mfma_f32_16x16x32_bf16 v[20:23], v[186:189], v[210:213], v[20:23]
	v_mfma_f32_16x16x32_bf16 v[8:11], v[166:169], v[218:221], v[8:11]
	v_mfma_f32_16x16x32_bf16 v[4:7], v[186:189], v[218:221], v[4:7]
	s_setprio 0
	s_barrier
	s_add_i32 s63, s63, 2
	s_add_u32 s28, s28, 0x100
	s_addc_u32 s29, s29, 0
	s_cmp_gt_u32 s63, 13
	s_mov_b64 s[42:43], s[44:45]

.LBB0_500:
	s_add_u32 s44, s42, 0x100
	s_addc_u32 s45, s43, 0
	s_cmp_eq_u32 s63, 12
	s_cselect_b32 s50, s26, s44
	s_cselect_b32 s51, s5, s45
	s_cselect_b32 s48, s27, s28
	s_cselect_b32 s49, s23, s29
	s_add_i32 s64, 0, 0x10000
	v_add_u32_e32 v138, s64, v3
	s_add_i32 s65, 0, 0x14000
	ds_read_b128 v[146:149], v138
	ds_read_b128 v[150:153], v138 offset:1024
	ds_read_b128 v[154:157], v138 offset:2048
	ds_read_b128 v[158:161], v138 offset:3072
	v_add_u32_e32 v138, s65, v3
	ds_read_b128 v[162:165], v138
	ds_read_b128 v[166:169], v138 offset:1024
	ds_read_b128 v[170:173], v138 offset:2048
	ds_read_b128 v[186:189], v138 offset:3072
	s_add_u32 s46, s42, 0x80
	s_addc_u32 s47, s43, 0
	s_add_u32 s42, s42, 0x40080
	s_addc_u32 s43, s43, 0
	s_mov_b32 m0, s60
	s_nop 0
	global_load_lds_dwordx4 v144, s[46:47]
	s_mov_b32 m0, s61
	s_nop 0
	global_load_lds_dwordx4 v140, s[46:47]
	s_add_i32 m0, s56, 0xc000
	s_nop 0
	global_load_lds_dwordx4 v144, s[42:43]
	s_add_i32 m0, s56, 0xe000
	s_nop 0
	global_load_lds_dwordx4 v140, s[42:43]
	ds_read_b128 v[190:193], v132
	ds_read_b128 v[194:197], v132 offset:1024
	ds_read_b128 v[198:201], v132 offset:2048
	ds_read_b128 v[202:205], v132 offset:3072
	ds_read_b128 v[206:209], v132 offset:4096
	ds_read_b128 v[210:213], v132 offset:5120
	ds_read_b128 v[214:217], v132 offset:6144
	ds_read_b128 v[218:221], v132 offset:7168
	s_waitcnt vmcnt(8)
	s_waitcnt lgkmcnt(8)
	s_barrier
	s_setprio 1
	s_waitcnt lgkmcnt(0)
	v_mfma_f32_16x16x32_bf16 v[128:131], v[146:149], v[190:193], v[128:131]
	v_mfma_f32_16x16x32_bf16 v[124:127], v[154:157], v[190:193], v[124:127]
	v_mfma_f32_16x16x32_bf16 v[112:115], v[146:149], v[198:201], v[112:115]
	v_mfma_f32_16x16x32_bf16 v[108:111], v[154:157], v[198:201], v[108:111]
	v_mfma_f32_16x16x32_bf16 v[96:99], v[146:149], v[206:209], v[96:99]
	v_mfma_f32_16x16x32_bf16 v[92:95], v[154:157], v[206:209], v[92:95]
	v_mfma_f32_16x16x32_bf16 v[80:83], v[146:149], v[214:217], v[80:83]
	v_mfma_f32_16x16x32_bf16 v[76:79], v[154:157], v[214:217], v[76:79]
	v_mfma_f32_16x16x32_bf16 v[128:131], v[150:153], v[194:197], v[128:131]
	v_mfma_f32_16x16x32_bf16 v[124:127], v[158:161], v[194:197], v[124:127]
	v_mfma_f32_16x16x32_bf16 v[112:115], v[150:153], v[202:205], v[112:115]
	v_mfma_f32_16x16x32_bf16 v[108:111], v[158:161], v[202:205], v[108:111]
	v_mfma_f32_16x16x32_bf16 v[96:99], v[150:153], v[210:213], v[96:99]
	v_mfma_f32_16x16x32_bf16 v[92:95], v[158:161], v[210:213], v[92:95]
	v_mfma_f32_16x16x32_bf16 v[80:83], v[150:153], v[218:221], v[80:83]
	v_mfma_f32_16x16x32_bf16 v[76:79], v[158:161], v[218:221], v[76:79]
	s_setprio 0
	s_setprio 1
	v_mfma_f32_16x16x32_bf16 v[120:123], v[162:165], v[190:193], v[120:123]
	v_mfma_f32_16x16x32_bf16 v[116:119], v[170:173], v[190:193], v[116:119]
	v_mfma_f32_16x16x32_bf16 v[104:107], v[162:165], v[198:201], v[104:107]
	v_mfma_f32_16x16x32_bf16 v[100:103], v[170:173], v[198:201], v[100:103]
	v_mfma_f32_16x16x32_bf16 v[88:91], v[162:165], v[206:209], v[88:91]
	v_mfma_f32_16x16x32_bf16 v[84:87], v[170:173], v[206:209], v[84:87]
	v_mfma_f32_16x16x32_bf16 v[72:75], v[162:165], v[214:217], v[72:75]
	v_mfma_f32_16x16x32_bf16 v[68:71], v[170:173], v[214:217], v[68:71]
	v_mfma_f32_16x16x32_bf16 v[120:123], v[166:169], v[194:197], v[120:123]
	v_mfma_f32_16x16x32_bf16 v[116:119], v[186:189], v[194:197], v[116:119]
	v_mfma_f32_16x16x32_bf16 v[104:107], v[166:169], v[202:205], v[104:107]
	v_mfma_f32_16x16x32_bf16 v[100:103], v[186:189], v[202:205], v[100:103]
	v_mfma_f32_16x16x32_bf16 v[88:91], v[166:169], v[210:213], v[88:91]
	v_mfma_f32_16x16x32_bf16 v[84:87], v[186:189], v[210:213], v[84:87]
	v_mfma_f32_16x16x32_bf16 v[72:75], v[166:169], v[218:221], v[72:75]
	v_mfma_f32_16x16x32_bf16 v[68:71], v[186:189], v[218:221], v[68:71]
	s_setprio 0
	s_barrier
	s_add_i32 s42, s64, s69
	s_mov_b32 m0, s42
	s_nop 0
	global_load_lds_dwordx4 v142, s[48:49]
	s_add_i32 m0, s42, 0x2000
	s_add_u32 s42, s48, 0x40000
	s_addc_u32 s43, s49, 0
	s_add_i32 s64, s65, s69
	global_load_lds_dwordx4 v0, s[48:49]
	s_mov_b32 m0, s64
	s_nop 0
	global_load_lds_dwordx4 v142, s[42:43]
	s_add_i32 m0, s64, 0x2000
	s_nop 0
	global_load_lds_dwordx4 v0, s[42:43]
	ds_read_b128 v[190:193], v132 offset:16384
	ds_read_b128 v[194:197], v132 offset:17408
	ds_read_b128 v[198:201], v132 offset:18432
	ds_read_b128 v[202:205], v132 offset:19456
	ds_read_b128 v[206:209], v132 offset:20480
	ds_read_b128 v[210:213], v132 offset:21504
	ds_read_b128 v[214:217], v132 offset:22528
	ds_read_b128 v[218:221], v132 offset:23552
	s_waitcnt vmcnt(4)
	s_waitcnt lgkmcnt(0)
	s_barrier
	s_setprio 1
	s_waitcnt lgkmcnt(0)
	v_mfma_f32_16x16x32_bf16 v[64:67], v[146:149], v[190:193], v[64:67]
	v_mfma_f32_16x16x32_bf16 v[60:63], v[154:157], v[190:193], v[60:63]
	v_mfma_f32_16x16x32_bf16 v[48:51], v[146:149], v[198:201], v[48:51]
	v_mfma_f32_16x16x32_bf16 v[44:47], v[154:157], v[198:201], v[44:47]
	v_mfma_f32_16x16x32_bf16 v[32:35], v[146:149], v[206:209], v[32:35]
	v_mfma_f32_16x16x32_bf16 v[28:31], v[154:157], v[206:209], v[28:31]
	v_mfma_f32_16x16x32_bf16 v[16:19], v[146:149], v[214:217], v[16:19]
	v_mfma_f32_16x16x32_bf16 v[12:15], v[154:157], v[214:217], v[12:15]
	v_mfma_f32_16x16x32_bf16 v[64:67], v[150:153], v[194:197], v[64:67]
	v_mfma_f32_16x16x32_bf16 v[60:63], v[158:161], v[194:197], v[60:63]
	v_mfma_f32_16x16x32_bf16 v[48:51], v[150:153], v[202:205], v[48:51]
	v_mfma_f32_16x16x32_bf16 v[44:47], v[158:161], v[202:205], v[44:47]
	v_mfma_f32_16x16x32_bf16 v[32:35], v[150:153], v[210:213], v[32:35]
	v_mfma_f32_16x16x32_bf16 v[28:31], v[158:161], v[210:213], v[28:31]
	v_mfma_f32_16x16x32_bf16 v[16:19], v[150:153], v[218:221], v[16:19]
	v_mfma_f32_16x16x32_bf16 v[12:15], v[158:161], v[218:221], v[12:15]
	s_setprio 0
	s_setprio 1
	v_mfma_f32_16x16x32_bf16 v[56:59], v[162:165], v[190:193], v[56:59]
	v_mfma_f32_16x16x32_bf16 v[52:55], v[170:173], v[190:193], v[52:55]
	v_mfma_f32_16x16x32_bf16 v[40:43], v[162:165], v[198:201], v[40:43]
	v_mfma_f32_16x16x32_bf16 v[36:39], v[170:173], v[198:201], v[36:39]
	v_mfma_f32_16x16x32_bf16 v[24:27], v[162:165], v[206:209], v[24:27]
	v_mfma_f32_16x16x32_bf16 v[20:23], v[170:173], v[206:209], v[20:23]
	v_mfma_f32_16x16x32_bf16 v[8:11], v[162:165], v[214:217], v[8:11]
	v_mfma_f32_16x16x32_bf16 v[4:7], v[170:173], v[214:217], v[4:7]
	v_mfma_f32_16x16x32_bf16 v[56:59], v[166:169], v[194:197], v[56:59]
	v_mfma_f32_16x16x32_bf16 v[52:55], v[186:189], v[194:197], v[52:55]
	v_mfma_f32_16x16x32_bf16 v[40:43], v[166:169], v[202:205], v[40:43]
	v_mfma_f32_16x16x32_bf16 v[36:39], v[186:189], v[202:205], v[36:39]
	v_mfma_f32_16x16x32_bf16 v[24:27], v[166:169], v[210:213], v[24:27]
	v_mfma_f32_16x16x32_bf16 v[20:23], v[186:189], v[210:213], v[20:23]
	v_mfma_f32_16x16x32_bf16 v[8:11], v[166:169], v[218:221], v[8:11]
	v_mfma_f32_16x16x32_bf16 v[4:7], v[186:189], v[218:221], v[4:7]
	s_setprio 0
	s_barrier
	s_add_i32 s64, 0, 0x18000
	v_add_u32_e32 v138, s64, v3
	s_add_i32 s65, 0, 0x1c000
	ds_read_b128 v[146:149], v138
	ds_read_b128 v[150:153], v138 offset:1024
	ds_read_b128 v[154:157], v138 offset:2048
	ds_read_b128 v[158:161], v138 offset:3072
	v_add_u32_e32 v138, s65, v3
	ds_read_b128 v[162:165], v138
	ds_read_b128 v[166:169], v138 offset:1024
	ds_read_b128 v[170:173], v138 offset:2048
	ds_read_b128 v[186:189], v138 offset:3072
	s_add_u32 s42, s50, 0x40000
	s_addc_u32 s43, s51, 0
	s_mov_b32 m0, s56
	s_nop 0
	global_load_lds_dwordx4 v144, s[50:51]
	s_mov_b32 m0, s57
	s_nop 0
	global_load_lds_dwordx4 v140, s[50:51]
	s_mov_b32 m0, s58
	s_nop 0
	global_load_lds_dwordx4 v144, s[42:43]
	s_mov_b32 m0, s59
	s_nop 0
	global_load_lds_dwordx4 v140, s[42:43]
	ds_read_b128 v[190:193], v132 offset:32768
	ds_read_b128 v[194:197], v132 offset:33792
	ds_read_b128 v[198:201], v132 offset:34816
	ds_read_b128 v[202:205], v132 offset:35840
	ds_read_b128 v[206:209], v132 offset:36864
	ds_read_b128 v[210:213], v132 offset:37888
	ds_read_b128 v[214:217], v132 offset:38912
	ds_read_b128 v[218:221], v132 offset:39936
	s_waitcnt vmcnt(8)
	s_waitcnt lgkmcnt(8)
	s_barrier
	s_setprio 1
	s_waitcnt lgkmcnt(0)
	v_mfma_f32_16x16x32_bf16 v[128:131], v[146:149], v[190:193], v[128:131]
	v_mfma_f32_16x16x32_bf16 v[124:127], v[154:157], v[190:193], v[124:127]
	v_mfma_f32_16x16x32_bf16 v[112:115], v[146:149], v[198:201], v[112:115]
	v_mfma_f32_16x16x32_bf16 v[108:111], v[154:157], v[198:201], v[108:111]
	v_mfma_f32_16x16x32_bf16 v[96:99], v[146:149], v[206:209], v[96:99]
	v_mfma_f32_16x16x32_bf16 v[92:95], v[154:157], v[206:209], v[92:95]
	v_mfma_f32_16x16x32_bf16 v[80:83], v[146:149], v[214:217], v[80:83]
	v_mfma_f32_16x16x32_bf16 v[76:79], v[154:157], v[214:217], v[76:79]
	v_mfma_f32_16x16x32_bf16 v[128:131], v[150:153], v[194:197], v[128:131]
	v_mfma_f32_16x16x32_bf16 v[124:127], v[158:161], v[194:197], v[124:127]
	v_mfma_f32_16x16x32_bf16 v[112:115], v[150:153], v[202:205], v[112:115]
	v_mfma_f32_16x16x32_bf16 v[108:111], v[158:161], v[202:205], v[108:111]
	v_mfma_f32_16x16x32_bf16 v[96:99], v[150:153], v[210:213], v[96:99]
	v_mfma_f32_16x16x32_bf16 v[92:95], v[158:161], v[210:213], v[92:95]
	v_mfma_f32_16x16x32_bf16 v[80:83], v[150:153], v[218:221], v[80:83]
	v_mfma_f32_16x16x32_bf16 v[76:79], v[158:161], v[218:221], v[76:79]
	s_setprio 0
	s_setprio 1
	v_mfma_f32_16x16x32_bf16 v[120:123], v[162:165], v[190:193], v[120:123]
	v_mfma_f32_16x16x32_bf16 v[116:119], v[170:173], v[190:193], v[116:119]
	v_mfma_f32_16x16x32_bf16 v[104:107], v[162:165], v[198:201], v[104:107]
	v_mfma_f32_16x16x32_bf16 v[100:103], v[170:173], v[198:201], v[100:103]
	v_mfma_f32_16x16x32_bf16 v[88:91], v[162:165], v[206:209], v[88:91]
	v_mfma_f32_16x16x32_bf16 v[84:87], v[170:173], v[206:209], v[84:87]
	v_mfma_f32_16x16x32_bf16 v[72:75], v[162:165], v[214:217], v[72:75]
	v_mfma_f32_16x16x32_bf16 v[68:71], v[170:173], v[214:217], v[68:71]
	v_mfma_f32_16x16x32_bf16 v[120:123], v[166:169], v[194:197], v[120:123]
	v_mfma_f32_16x16x32_bf16 v[116:119], v[186:189], v[194:197], v[116:119]
	v_mfma_f32_16x16x32_bf16 v[104:107], v[166:169], v[202:205], v[104:107]
	v_mfma_f32_16x16x32_bf16 v[100:103], v[186:189], v[202:205], v[100:103]
	v_mfma_f32_16x16x32_bf16 v[88:91], v[166:169], v[210:213], v[88:91]
	v_mfma_f32_16x16x32_bf16 v[84:87], v[186:189], v[210:213], v[84:87]
	v_mfma_f32_16x16x32_bf16 v[72:75], v[166:169], v[218:221], v[72:75]
	v_mfma_f32_16x16x32_bf16 v[68:71], v[186:189], v[218:221], v[68:71]
	s_setprio 0
	s_barrier
	s_add_u32 s42, s48, 0x80
	s_addc_u32 s43, s49, 0
	s_add_i32 s50, s64, s69
	s_mov_b32 m0, s50
	s_nop 0
	global_load_lds_dwordx4 v142, s[42:43]
	s_add_i32 m0, s50, 0x2000
	s_nop 0
	global_load_lds_dwordx4 v0, s[42:43]
	s_add_u32 s42, s48, 0x40080
	s_addc_u32 s43, s49, 0
	s_add_i32 s48, s65, s69
	s_mov_b32 m0, s48
	s_nop 0
	global_load_lds_dwordx4 v142, s[42:43]
	s_add_i32 m0, s48, 0x2000
	s_nop 0
	global_load_lds_dwordx4 v0, s[42:43]
	ds_read_b128 v[190:193], v132 offset:49152
	ds_read_b128 v[194:197], v132 offset:50176
	ds_read_b128 v[198:201], v132 offset:51200
	ds_read_b128 v[202:205], v132 offset:52224
	ds_read_b128 v[206:209], v132 offset:53248
	ds_read_b128 v[210:213], v132 offset:54272
	ds_read_b128 v[214:217], v132 offset:55296
	ds_read_b128 v[218:221], v132 offset:56320
	s_waitcnt vmcnt(4)
	s_waitcnt lgkmcnt(0)
	s_barrier
	s_setprio 1
	s_waitcnt lgkmcnt(0)
	v_mfma_f32_16x16x32_bf16 v[64:67], v[146:149], v[190:193], v[64:67]
	v_mfma_f32_16x16x32_bf16 v[60:63], v[154:157], v[190:193], v[60:63]
	v_mfma_f32_16x16x32_bf16 v[48:51], v[146:149], v[198:201], v[48:51]
	v_mfma_f32_16x16x32_bf16 v[44:47], v[154:157], v[198:201], v[44:47]
	v_mfma_f32_16x16x32_bf16 v[32:35], v[146:149], v[206:209], v[32:35]
	v_mfma_f32_16x16x32_bf16 v[28:31], v[154:157], v[206:209], v[28:31]
	v_mfma_f32_16x16x32_bf16 v[16:19], v[146:149], v[214:217], v[16:19]
	v_mfma_f32_16x16x32_bf16 v[12:15], v[154:157], v[214:217], v[12:15]
	v_mfma_f32_16x16x32_bf16 v[64:67], v[150:153], v[194:197], v[64:67]
	v_mfma_f32_16x16x32_bf16 v[60:63], v[158:161], v[194:197], v[60:63]
	v_mfma_f32_16x16x32_bf16 v[48:51], v[150:153], v[202:205], v[48:51]
	v_mfma_f32_16x16x32_bf16 v[44:47], v[158:161], v[202:205], v[44:47]
	v_mfma_f32_16x16x32_bf16 v[32:35], v[150:153], v[210:213], v[32:35]
	v_mfma_f32_16x16x32_bf16 v[28:31], v[158:161], v[210:213], v[28:31]
	v_mfma_f32_16x16x32_bf16 v[16:19], v[150:153], v[218:221], v[16:19]
	v_mfma_f32_16x16x32_bf16 v[12:15], v[158:161], v[218:221], v[12:15]
	s_setprio 0
	s_setprio 1
	v_mfma_f32_16x16x32_bf16 v[56:59], v[162:165], v[190:193], v[56:59]
	v_mfma_f32_16x16x32_bf16 v[52:55], v[170:173], v[190:193], v[52:55]
	v_mfma_f32_16x16x32_bf16 v[40:43], v[162:165], v[198:201], v[40:43]
	v_mfma_f32_16x16x32_bf16 v[36:39], v[170:173], v[198:201], v[36:39]
	v_mfma_f32_16x16x32_bf16 v[24:27], v[162:165], v[206:209], v[24:27]
	v_mfma_f32_16x16x32_bf16 v[20:23], v[170:173], v[206:209], v[20:23]
	v_mfma_f32_16x16x32_bf16 v[8:11], v[162:165], v[214:217], v[8:11]
	v_mfma_f32_16x16x32_bf16 v[4:7], v[170:173], v[214:217], v[4:7]
	v_mfma_f32_16x16x32_bf16 v[56:59], v[166:169], v[194:197], v[56:59]
	v_mfma_f32_16x16x32_bf16 v[52:55], v[186:189], v[194:197], v[52:55]
	v_mfma_f32_16x16x32_bf16 v[40:43], v[166:169], v[202:205], v[40:43]
	v_mfma_f32_16x16x32_bf16 v[36:39], v[186:189], v[202:205], v[36:39]
	v_mfma_f32_16x16x32_bf16 v[24:27], v[166:169], v[210:213], v[24:27]
	v_mfma_f32_16x16x32_bf16 v[20:23], v[186:189], v[210:213], v[20:23]
	v_mfma_f32_16x16x32_bf16 v[8:11], v[166:169], v[218:221], v[8:11]
	v_mfma_f32_16x16x32_bf16 v[4:7], v[186:189], v[218:221], v[4:7]
	s_setprio 0
	s_barrier
	s_add_i32 s63, s63, 2
	s_add_u32 s28, s28, 0x100
	s_addc_u32 s29, s29, 0
	s_cmp_gt_u32 s63, 13
	s_mov_b64 s[42:43], s[44:45]
	s_cbranch_scc0 .LBB0_500
	s_and_b64 vcc, exec, s[14:15]
	s_cbranch_vccz .LBB0_503
	s_barrier
